# MLA rotated loop edge with the three next-tile K/V prefetch loads issued before the loop barrier instead of after it
# speedup vs baseline: 1.0023x; 1.0023x over previous
; #define LAS __attribute__((address_space(3)))
; #define MFMA32(a, b, c) __builtin_amdgcn_mfma_f32_32x32x16_bf16((a), (b), (c), 0, 0, 0)
; __device__ __forceinline__ void mla_unit2(LAS unsigned char* lds, const bf16_t* QB, const bf16_t* KB, const bf16_t* VT, bf16_t* OB, int b, int h, int qb, int wv) {
;     ...
;     for (int t = 0; t < ntiles; ++t) {
;         LAS unsigned char* cur = lds + (t & 1) * M2BUF;
;         { const int tn = (t + 1 < tl) ? t + 1 : tl;
;           ra = *(const u32x4*)(gKA + (size_t)tn * 64 * NQB); rc = *(const u32x4*)(gKC + (size_t)tn * 64 * NQB); rv = *(const u32x4*)(gV + tn * 64); }
;         if (t < nact) {
;             const int k0 = t * 64;
;             f32x16 sa0, sa1, sb0, sb1;
;             { const LAS unsigned char* kp = cur + r * MK_ROW + hh * 16;
; #pragma unroll
;               for (int i = 0; i < 16; ++i) { sa0[i] = 0.f; sa1[i] = 0.f; sb0[i] = 0.f; sb1[i] = 0.f; }
; #pragma unroll
;               for (int hf = 0; hf < 2; ++hf) {
;                   bf16x8 ka[3], kc[3];
; #pragma unroll
;                   for (int s = 0; s < 3; ++s) { ka[s] = *(const LAS bf16x8*)(kp + (3 * hf + s) * 32); kc[s] = *(const LAS bf16x8*)(kp + 32 * MK_ROW + (3 * hf + s) * 32); }
;                   __builtin_amdgcn_sched_barrier(0);
; #pragma unroll
;                   for (int s = 0; s < 3; ++s) { sa0 = MFMA32(ka[s], qa[3 * hf + s], sa0); sa1 = MFMA32(kc[s], qa[3 * hf + s], sa1); sb0 = MFMA32(ka[s], qbf[3 * hf + s], sb0); sb1 = MFMA32(kc[s], qbf[3 * hf + s], sb1); }
;                   __builtin_amdgcn_sched_barrier(0);
;               } }
.Lmla_head:
	global_load_dwordx4 v[6:9], v[192:193], off
	s_nop 0
	global_load_dwordx4 v[2:5], v[194:195], off
	global_load_dwordx4 v[10:13], v[226:227], off
.Lmla_top2:
	s_cmp_gt_i32 s0, s72
	s_cbranch_scc1 .LBB0_676
	s_bitcmp1_b32 s0, 0
	s_cselect_b32 s0, 0x5800, 0
	s_add_i32 s12, s0, 0
	v_add3_u32 v0, s12, v209, v206
	ds_read_b128 v[80:83], v0
	ds_read_b128 v[226:229], v0 offset:32
	ds_read_b128 v[84:87], v0 offset:6656
	ds_read_b128 v[230:233], v0 offset:64
	ds_read_b128 v[234:237], v0 offset:6688
	ds_read_b128 v[238:241], v0 offset:6720
	s_waitcnt vmcnt(14) lgkmcnt(5)
	v_mfma_f32_32x32x16_bf16 v[128:143], v[80:83], v[144:147], 0
	s_waitcnt lgkmcnt(3)
	v_mfma_f32_32x32x16_bf16 v[112:127], v[84:87], v[144:147], 0
	s_waitcnt vmcnt(5)
	v_mfma_f32_32x32x16_bf16 v[96:111], v[80:83], v[180:183], 0
	v_mfma_f32_32x32x16_bf16 v[80:95], v[84:87], v[180:183], 0
	v_mfma_f32_32x32x16_bf16 v[128:143], v[226:229], v[148:151], v[128:143]
	s_waitcnt lgkmcnt(1)
	v_mfma_f32_32x32x16_bf16 v[112:127], v[234:237], v[148:151], v[112:127]
	v_mfma_f32_32x32x16_bf16 v[96:111], v[226:229], v[156:159], v[96:111]
	v_mfma_f32_32x32x16_bf16 v[80:95], v[234:237], v[156:159], v[80:95]
	v_mfma_f32_32x32x16_bf16 v[128:143], v[230:233], v[152:155], v[128:143]
	s_waitcnt lgkmcnt(0)
	v_mfma_f32_32x32x16_bf16 v[112:127], v[238:241], v[152:155], v[112:127]
	v_mfma_f32_32x32x16_bf16 v[96:111], v[230:233], v[160:163], v[96:111]
	v_mfma_f32_32x32x16_bf16 v[80:95], v[238:241], v[160:163], v[80:95]
	ds_read_b128 v[226:229], v0 offset:96
	ds_read_b128 v[230:233], v0 offset:128
	ds_read_b128 v[234:237], v0 offset:6752
	ds_read_b128 v[238:241], v0 offset:160
	ds_read_b128 v[242:245], v0 offset:6784
	ds_read_b128 v[246:249], v0 offset:6816
	s_waitcnt lgkmcnt(5)
	v_mfma_f32_32x32x16_bf16 v[128:143], v[226:229], v[164:167], v[128:143]
	s_waitcnt lgkmcnt(3)
	v_mfma_f32_32x32x16_bf16 v[112:127], v[234:237], v[164:167], v[112:127]
	v_mfma_f32_32x32x16_bf16 v[96:111], v[226:229], v[172:175], v[96:111]
	v_mfma_f32_32x32x16_bf16 v[80:95], v[234:237], v[172:175], v[80:95]
	v_mfma_f32_32x32x16_bf16 v[128:143], v[230:233], v[168:171], v[128:143]
	s_waitcnt lgkmcnt(1)
	v_mfma_f32_32x32x16_bf16 v[112:127], v[242:245], v[168:171], v[112:127]
	v_mfma_f32_32x32x16_bf16 v[96:111], v[230:233], v[176:179], v[96:111]
	v_mfma_f32_32x32x16_bf16 v[80:95], v[242:245], v[176:179], v[80:95]
	s_waitcnt vmcnt(4)
	v_mfma_f32_32x32x16_bf16 v[128:143], v[238:241], v[184:187], v[128:143]
	s_waitcnt lgkmcnt(0)
	v_mfma_f32_32x32x16_bf16 v[112:127], v[246:249], v[184:187], v[112:127]
	s_waitcnt vmcnt(3)
	v_mfma_f32_32x32x16_bf16 v[96:111], v[238:241], v[188:191], v[96:111]
	v_mfma_f32_32x32x16_bf16 v[80:95], v[246:249], v[188:191], v[80:95]
	s_add_i32 s25, s71, 63
	s_cmp_le_i32 s25, s70
	s_nop 7
	s_cbranch_scc1 .Lmla_nomask
	s_cmp_eq_u32 s100, 0
	s_cbranch_scc1 .Lmla_m663
	s_mov_b32 s100, 0
	s_cmp_lg_u32 s71, 0
	s_cbranch_scc1 .Lmla_m663
	v_mov_b32_e32 v224, 0xff800000
	v_mov_b32_e32 v223, 0xff800000

; #define LAS __attribute__((address_space(3)))
; __device__ __forceinline__ void mla_unit2(LAS unsigned char* lds, const bf16_t* QB, const bf16_t* KB, const bf16_t* VT, bf16_t* OB, int b, int h, int qb, int wv) {
;     ...
;     for (int t = 0; t < ntiles; ++t) {
;         LAS unsigned char* cur = lds + (t & 1) * M2BUF;
;         { const int tn = (t + 1 < tl) ? t + 1 : tl;
;           ra = *(const u32x4*)(gKA + (size_t)tn * 64 * NQB); rc = *(const u32x4*)(gKC + (size_t)tn * 64 * NQB); rv = *(const u32x4*)(gV + tn * 64); }
;     ...
;         { LAS unsigned char* nxt = lds + ((t + 1) & 1) * M2BUF;
;           *(LAS u32x4*)(nxt + lKA) = ra; *(LAS u32x4*)(nxt + lKC) = rc; *(LAS u32x4*)(nxt + lV) = rv; }
;         __syncthreads();
.LBB0_676:
	s_bitcmp1_b32 s76, 0
	s_cselect_b32 s0, 0x5800, 0
	s_add_i32 s0, s0, 0
	v_add_u32_e32 v0, s0, v197
	s_waitcnt vmcnt(2)
	ds_write_b128 v0, v[6:9]
	v_add_u32_e32 v0, s0, v207
	s_add_i32 s71, s71, 64
	s_waitcnt vmcnt(1)
	ds_write_b128 v0, v[2:5]
	v_add_u32_e32 v0, s0, v208
	s_waitcnt vmcnt(0)
	ds_write_b128 v0, v[10:13] offset:13312
	s_mov_b32 s0, s76
	s_add_i32 s76, s0, 1
	s_min_u32 s1, s76, s73
	s_mul_i32 s12, s1, 0x18000
	v_lshl_add_u64 v[192:193], v[200:201], 0, s[12:13]
	v_lshl_add_u64 v[194:195], v[202:203], 0, s[12:13]
	s_lshl_b32 s12, s1, 7
	v_lshl_add_u64 v[226:227], v[204:205], 0, s[12:13]
	s_cmp_lg_u32 s75, s71
	s_waitcnt lgkmcnt(0)
	s_cbranch_scc0 .Lmla_exitbar
	global_load_dwordx4 v[6:9], v[192:193], off
	s_nop 0
	global_load_dwordx4 v[2:5], v[194:195], off
	global_load_dwordx4 v[10:13], v[226:227], off
	s_barrier
	s_branch .Lmla_top2
.Lmla_exitbar:
	s_barrier
	s_branch .LBB0_659
